# dilated attention: all 40 QK and all 40 PV MFMAs take their LDS fragment one MFMA ahead (spare quads v244-247 / v232-235)
# speedup vs baseline: 1.0046x; 1.0046x over previous
.LBB0_100:
	v_add_co_u32_e32 v8, vcc, 0x8000, v4
	s_mov_b32 s1, 0x10000
	s_nop 0
	v_addc_co_u32_e32 v9, vcc, 0, v5, vcc
	global_load_dwordx4 v[146:149], v[8:9], off
	v_add_co_u32_e32 v8, vcc, 0xa000, v4
	s_nop 1
	v_addc_co_u32_e32 v9, vcc, 0, v5, vcc
	global_load_dwordx4 v[150:153], v[8:9], off
	v_add_co_u32_e32 v8, vcc, 0xc000, v4
	s_nop 1
	v_addc_co_u32_e32 v9, vcc, 0, v5, vcc
	global_load_dwordx4 v[154:157], v[8:9], off
	v_add_co_u32_e32 v8, vcc, 0xe000, v4
	s_nop 1
	v_addc_co_u32_e32 v9, vcc, 0, v5, vcc
	global_load_dwordx4 v[158:161], v[8:9], off
	v_add_co_u32_e32 v8, vcc, s1, v4
	s_add_i32 s1, 0, 0x18000
	s_nop 0
	v_addc_co_u32_e32 v9, vcc, 0, v5, vcc
	global_load_dwordx4 v[162:165], v[8:9], off
	v_add_co_u32_e32 v8, vcc, 0x12000, v4
	s_cmp_eq_u32 s81, 0
	s_nop 0
	v_addc_co_u32_e32 v9, vcc, 0, v5, vcc
	global_load_dwordx4 v[166:169], v[8:9], off
	v_add_co_u32_e32 v8, vcc, 0x14000, v4
	s_cselect_b64 s[6:7], -1, 0
	s_nop 0
	v_addc_co_u32_e32 v9, vcc, 0, v5, vcc
	v_add_co_u32_e32 v4, vcc, 0x16000, v4
	global_load_dwordx4 v[170:173], v[8:9], off
	s_nop 0
	v_addc_co_u32_e32 v5, vcc, 0, v5, vcc
	global_load_dwordx4 v[174:177], v[4:5], off
	v_lshlrev_b32_e32 v4, 2, v6
	v_and_b32_e32 v4, 12, v4
	v_bfe_u32 v5, v6, 2, 2
	v_or_b32_e32 v8, v4, v5
	v_bitop3_b32 v4, v4, v226, v5 bitop3:0x36
	v_lshl_add_u32 v9, v227, 8, s80
	v_lshl_add_u32 v10, v4, 4, v9
	v_bitop3_b32 v232, v226, v8, 2 bitop3:0x36
	v_lshl_add_u32 v232, v232, 4, v9
	v_bitop3_b32 v236, v226, v8, 4 bitop3:0x36
	v_lshl_add_u32 v236, v236, 4, v9
	v_bitop3_b32 v237, v226, v8, 6 bitop3:0x36
	v_lshl_add_u32 v237, v237, 4, v9
	v_bitop3_b32 v238, v226, v8, 8 bitop3:0x36
	v_lshl_add_u32 v238, v238, 4, v9
	v_bitop3_b32 v239, v226, v8, 10 bitop3:0x36
	v_lshl_add_u32 v239, v239, 4, v9
	v_bitop3_b32 v240, v226, v8, 12 bitop3:0x36
	v_lshl_add_u32 v240, v240, 4, v9
	v_bitop3_b32 v100, v226, v8, 14 bitop3:0x36
	v_lshl_add_u32 v100, v100, 4, v9
	ds_read_b128 v[4:7], v10
	ds_read_b128 v[244:247], v232
	s_waitcnt vmcnt(15) lgkmcnt(1)
	v_mfma_f32_32x32x16_bf16 v[64:79], v[4:7], v[0:3], 0
	s_and_b64 s[28:29], s[12:13], s[6:7]
	s_and_b64 vcc, exec, s[28:29]
	ds_read_b128 v[4:7], v236
	s_waitcnt vmcnt(14) lgkmcnt(1)
	v_mfma_f32_32x32x16_bf16 v[64:79], v[244:247], v[202:205], v[64:79]
	ds_read_b128 v[244:247], v237
	s_waitcnt vmcnt(13) lgkmcnt(1)
	v_mfma_f32_32x32x16_bf16 v[64:79], v[4:7], v[198:201], v[64:79]
	ds_read_b128 v[4:7], v238
	s_waitcnt vmcnt(12) lgkmcnt(1)
	v_mfma_f32_32x32x16_bf16 v[64:79], v[244:247], v[194:197], v[64:79]
	ds_read_b128 v[244:247], v239
	s_waitcnt vmcnt(11) lgkmcnt(1)
	v_mfma_f32_32x32x16_bf16 v[64:79], v[4:7], v[190:193], v[64:79]
	ds_read_b128 v[4:7], v240
	s_waitcnt vmcnt(10) lgkmcnt(1)
	v_mfma_f32_32x32x16_bf16 v[64:79], v[244:247], v[186:189], v[64:79]
	ds_read_b128 v[244:247], v100
	s_waitcnt vmcnt(9) lgkmcnt(1)
	v_mfma_f32_32x32x16_bf16 v[64:79], v[4:7], v[182:185], v[64:79]
	ds_read_b128 v[4:7], v10 offset:8192
	s_waitcnt vmcnt(8) lgkmcnt(1)
	v_mfma_f32_32x32x16_bf16 v[64:79], v[244:247], v[178:181], v[64:79]
	ds_read_b128 v[244:247], v232 offset:8192
	s_waitcnt lgkmcnt(1)
	v_mfma_f32_32x32x16_bf16 v[48:63], v[4:7], v[0:3], 0
	ds_read_b128 v[4:7], v236 offset:8192
	s_waitcnt lgkmcnt(1)
	v_mfma_f32_32x32x16_bf16 v[48:63], v[244:247], v[202:205], v[48:63]
	ds_read_b128 v[244:247], v237 offset:8192
	s_waitcnt lgkmcnt(1)
	v_mfma_f32_32x32x16_bf16 v[48:63], v[4:7], v[198:201], v[48:63]
	ds_read_b128 v[4:7], v238 offset:8192
	s_waitcnt lgkmcnt(1)
	v_mfma_f32_32x32x16_bf16 v[48:63], v[244:247], v[194:197], v[48:63]
	ds_read_b128 v[244:247], v239 offset:8192
	s_waitcnt lgkmcnt(1)
	v_mfma_f32_32x32x16_bf16 v[48:63], v[4:7], v[190:193], v[48:63]
	ds_read_b128 v[4:7], v240 offset:8192
	s_waitcnt lgkmcnt(1)
	v_mfma_f32_32x32x16_bf16 v[48:63], v[244:247], v[186:189], v[48:63]
	ds_read_b128 v[244:247], v100 offset:8192
	s_waitcnt lgkmcnt(1)
	v_mfma_f32_32x32x16_bf16 v[48:63], v[4:7], v[182:185], v[48:63]
	ds_read_b128 v[4:7], v10 offset:16384
	s_waitcnt lgkmcnt(1)
	v_mfma_f32_32x32x16_bf16 v[48:63], v[244:247], v[178:181], v[48:63]
	ds_read_b128 v[244:247], v232 offset:16384
	s_waitcnt lgkmcnt(1)
	v_mfma_f32_32x32x16_bf16 v[32:47], v[4:7], v[0:3], 0
	ds_read_b128 v[4:7], v236 offset:16384
	s_waitcnt lgkmcnt(1)
	v_mfma_f32_32x32x16_bf16 v[32:47], v[244:247], v[202:205], v[32:47]
	ds_read_b128 v[244:247], v237 offset:16384
	s_waitcnt lgkmcnt(1)
	v_mfma_f32_32x32x16_bf16 v[32:47], v[4:7], v[198:201], v[32:47]
	ds_read_b128 v[4:7], v238 offset:16384
	s_waitcnt lgkmcnt(1)
	v_mfma_f32_32x32x16_bf16 v[32:47], v[244:247], v[194:197], v[32:47]
	ds_read_b128 v[244:247], v239 offset:16384
	s_waitcnt lgkmcnt(1)
	v_mfma_f32_32x32x16_bf16 v[32:47], v[4:7], v[190:193], v[32:47]
	ds_read_b128 v[4:7], v240 offset:16384
	s_waitcnt lgkmcnt(1)
	v_mfma_f32_32x32x16_bf16 v[32:47], v[244:247], v[186:189], v[32:47]
	ds_read_b128 v[244:247], v100 offset:16384
	s_waitcnt lgkmcnt(1)
	v_mfma_f32_32x32x16_bf16 v[32:47], v[4:7], v[182:185], v[32:47]
	ds_read_b128 v[4:7], v10 offset:24576
	s_waitcnt lgkmcnt(1)
	v_mfma_f32_32x32x16_bf16 v[32:47], v[244:247], v[178:181], v[32:47]
	ds_read_b128 v[244:247], v232 offset:24576
	s_waitcnt lgkmcnt(1)
	v_mfma_f32_32x32x16_bf16 v[16:31], v[4:7], v[0:3], 0
	ds_read_b128 v[4:7], v236 offset:24576
	s_waitcnt lgkmcnt(1)
	v_mfma_f32_32x32x16_bf16 v[16:31], v[244:247], v[202:205], v[16:31]
	ds_read_b128 v[244:247], v237 offset:24576
	s_waitcnt lgkmcnt(1)
	v_mfma_f32_32x32x16_bf16 v[16:31], v[4:7], v[198:201], v[16:31]
	ds_read_b128 v[4:7], v238 offset:24576
	s_waitcnt lgkmcnt(1)
	v_mfma_f32_32x32x16_bf16 v[16:31], v[244:247], v[194:197], v[16:31]
	ds_read_b128 v[244:247], v239 offset:24576
	s_waitcnt lgkmcnt(1)
	v_mfma_f32_32x32x16_bf16 v[16:31], v[4:7], v[190:193], v[16:31]
	ds_read_b128 v[4:7], v240 offset:24576
	s_waitcnt lgkmcnt(1)
	v_mfma_f32_32x32x16_bf16 v[16:31], v[244:247], v[186:189], v[16:31]
	ds_read_b128 v[244:247], v100 offset:24576
	s_waitcnt lgkmcnt(1)
	v_mfma_f32_32x32x16_bf16 v[16:31], v[4:7], v[182:185], v[16:31]
	ds_read_b128 v[4:7], v10 offset:32768
	s_waitcnt lgkmcnt(1)
	v_mfma_f32_32x32x16_bf16 v[16:31], v[244:247], v[178:181], v[16:31]
	ds_read_b128 v[244:247], v232 offset:32768
	s_waitcnt lgkmcnt(1)
	v_mfma_f32_32x32x16_bf16 v[0:15], v[4:7], v[0:3], 0
	ds_read_b128 v[232:235], v236 offset:32768
	s_waitcnt lgkmcnt(1)
	v_mfma_f32_32x32x16_bf16 v[0:15], v[244:247], v[202:205], v[0:15]
	ds_read_b128 v[244:247], v237 offset:32768
	s_waitcnt lgkmcnt(1)
	v_mfma_f32_32x32x16_bf16 v[0:15], v[232:235], v[198:201], v[0:15]
	v_mov_b32_e32 v202, 0xff800000
	ds_read_b128 v[232:235], v238 offset:32768
	s_waitcnt lgkmcnt(1)
	v_mfma_f32_32x32x16_bf16 v[0:15], v[244:247], v[194:197], v[0:15]
	ds_read_b128 v[244:247], v239 offset:32768
	s_waitcnt lgkmcnt(1)
	v_mfma_f32_32x32x16_bf16 v[0:15], v[232:235], v[190:193], v[0:15]
	v_mov_b32_e32 v195, 0xff800000
	v_mov_b32_e32 v194, 0xff800000
	v_mov_b32_e32 v197, 0xff800000
	v_mov_b32_e32 v196, 0xff800000
	ds_read_b128 v[232:235], v240 offset:32768
	s_waitcnt lgkmcnt(1)
	v_mfma_f32_32x32x16_bf16 v[0:15], v[244:247], v[186:189], v[0:15]
	v_mov_b32_e32 v190, 0xff800000
	v_mov_b32_e32 v191, 0xff800000
	v_mov_b32_e32 v193, 0xff800000
	v_mov_b32_e32 v192, 0xff800000
	ds_read_b128 v[244:247], v100 offset:32768
	s_waitcnt lgkmcnt(1)
	v_mfma_f32_32x32x16_bf16 v[0:15], v[232:235], v[182:185], v[0:15]
	v_mov_b32_e32 v100, 0xff800000
	v_mov_b32_e32 v186, 0xff800000
	v_mov_b32_e32 v189, 0xff800000
	v_mov_b32_e32 v188, 0xff800000
	s_waitcnt lgkmcnt(0)
	v_mfma_f32_32x32x16_bf16 v[0:15], v[244:247], v[178:181], v[0:15]
	v_lshlrev_b32_e32 v180, 2, v226
	v_sub_u32_e32 v181, v227, v180
	v_lshl_add_u32 v187, v181, 2, s1
	v_mov_b32_e32 v178, 0xff800000
	v_mov_b32_e32 v182, 0xff800000
	v_mov_b32_e32 v184, 0xff800000
	v_mov_b32_e32 v183, 0xff800000
	v_mov_b32_e32 v185, 0xff800000
	s_cbranch_vccnz .LBB0_102
	ds_read2_b32 v[182:183], v187 offset0:159 offset1:160
	v_cmp_gt_i32_e32 vcc, 2, v181
	s_mov_b32 s1, 0xff800000
	s_waitcnt lgkmcnt(0)
	v_pk_add_f32 v[64:65], v[64:65], v[182:183] op_sel:[0,1] op_sel_hi:[1,0]
	s_nop 0
	v_cndmask_b32_e32 v100, v220, v65, vcc
	v_cmp_gt_i32_e32 vcc, 1, v181
	s_nop 1
	v_cndmask_b32_e32 v182, v220, v64, vcc
	ds_read2_b32 v[64:65], v187 offset0:157 offset1:158
	v_cmp_gt_i32_e32 vcc, 4, v181
	v_max3_f32 v179, v182, s1, v100
	s_waitcnt lgkmcnt(0)
	v_pk_add_f32 v[64:65], v[66:67], v[64:65] op_sel:[0,1] op_sel_hi:[1,0]
	s_nop 0
	v_cndmask_b32_e32 v183, v220, v65, vcc
	v_cmp_gt_i32_e32 vcc, 3, v181
	s_nop 1
	v_cndmask_b32_e32 v184, v220, v64, vcc
	ds_read2_b32 v[64:65], v187 offset0:151 offset1:152
	v_cmp_gt_i32_e32 vcc, 10, v181
	v_max3_f32 v66, v179, v184, v183
	s_waitcnt lgkmcnt(0)
	v_pk_add_f32 v[64:65], v[68:69], v[64:65] op_sel:[0,1] op_sel_hi:[1,0]
	s_nop 0
	v_cndmask_b32_e32 v185, v220, v65, vcc
	v_cmp_gt_i32_e32 vcc, 9, v181
	s_nop 1
	v_cndmask_b32_e32 v186, v220, v64, vcc
	ds_read2_b32 v[64:65], v187 offset0:149 offset1:150
	v_cmp_gt_i32_e32 vcc, 12, v181
	v_max3_f32 v66, v66, v186, v185
	s_waitcnt lgkmcnt(0)
	v_pk_add_f32 v[64:65], v[70:71], v[64:65] op_sel:[0,1] op_sel_hi:[1,0]
	s_nop 0
	v_cndmask_b32_e32 v188, v220, v65, vcc
	v_cmp_gt_i32_e32 vcc, 11, v181
	s_nop 1
	v_cndmask_b32_e32 v189, v220, v64, vcc
	ds_read2_b32 v[64:65], v187 offset0:143 offset1:144
	v_cmp_gt_i32_e32 vcc, 18, v181
	v_max3_f32 v66, v66, v189, v188
	s_waitcnt lgkmcnt(0)
	v_pk_add_f32 v[64:65], v[72:73], v[64:65] op_sel:[0,1] op_sel_hi:[1,0]
	s_nop 0
	v_cndmask_b32_e32 v191, v220, v65, vcc
	v_cmp_gt_i32_e32 vcc, 17, v181
	s_nop 1
	v_cndmask_b32_e32 v190, v220, v64, vcc
	ds_read2_b32 v[64:65], v187 offset0:141 offset1:142
	v_cmp_gt_i32_e32 vcc, 20, v181
	v_max3_f32 v66, v66, v190, v191
	s_waitcnt lgkmcnt(0)
	v_pk_add_f32 v[64:65], v[74:75], v[64:65] op_sel:[0,1] op_sel_hi:[1,0]
	s_nop 0
	v_cndmask_b32_e32 v192, v220, v65, vcc
	v_cmp_gt_i32_e32 vcc, 19, v181
	s_nop 1
	v_cndmask_b32_e32 v193, v220, v64, vcc
	ds_read2_b32 v[64:65], v187 offset0:135 offset1:136
	v_cmp_gt_i32_e32 vcc, 26, v181
	v_max3_f32 v66, v66, v193, v192
	s_waitcnt lgkmcnt(0)
	v_pk_add_f32 v[64:65], v[76:77], v[64:65] op_sel:[0,1] op_sel_hi:[1,0]
	s_nop 0
	v_cndmask_b32_e32 v194, v220, v65, vcc
	v_cmp_gt_i32_e32 vcc, 25, v181
	s_nop 1
	v_cndmask_b32_e32 v195, v220, v64, vcc
	ds_read2_b32 v[64:65], v187 offset0:133 offset1:134
	v_cmp_gt_i32_e32 vcc, 28, v181
	v_max3_f32 v66, v66, v195, v194
	s_waitcnt lgkmcnt(0)
	v_pk_add_f32 v[64:65], v[78:79], v[64:65] op_sel:[0,1] op_sel_hi:[1,0]
	s_nop 0
	v_cndmask_b32_e32 v196, v220, v65, vcc
	v_cmp_gt_i32_e32 vcc, 27, v181
	s_nop 1
	v_cndmask_b32_e32 v197, v220, v64, vcc
	v_max3_f32 v202, v66, v197, v196

.LBB0_127:
	s_lshl_b32 s6, s54, 10
	s_mul_i32 s1, s31, 0xc0000
	s_mul_hi_u32 s31, s30, 0xc0000
	s_ashr_i32 s7, s6, 31
	s_add_i32 s31, s31, s1
	s_and_b64 s[60:61], s[60:61], exec
	s_cselect_b32 s1, 4, 16
	s_and_b64 s[60:61], s[72:73], exec
	s_cselect_b32 s52, 1, s1
	s_lshl_b32 s1, s54, 3
	s_or_b32 s54, s1, s55
	s_mov_b32 s1, 0x8000
	v_add_co_u32_e32 v48, vcc, s1, v0
	s_mov_b32 s1, 0xa000
	s_nop 0
	v_addc_co_u32_e32 v49, vcc, 0, v1, vcc
	global_load_dwordx4 v[96:99], v[48:49], off
	v_add_co_u32_e32 v48, vcc, s1, v0
	s_mov_b32 s1, 0xc000
	s_nop 0
	v_addc_co_u32_e32 v49, vcc, 0, v1, vcc
	global_load_dwordx4 v[102:105], v[48:49], off
	v_add_co_u32_e32 v48, vcc, s1, v0
	s_mov_b32 s1, 0xe000
	s_nop 0
	v_addc_co_u32_e32 v49, vcc, 0, v1, vcc
	global_load_dwordx4 v[106:109], v[48:49], off
	v_add_co_u32_e32 v48, vcc, s1, v0
	s_mov_b32 s1, 0x10000
	s_nop 0
	v_addc_co_u32_e32 v49, vcc, 0, v1, vcc
	global_load_dwordx4 v[110:113], v[48:49], off
	v_add_co_u32_e32 v48, vcc, s1, v0
	s_mov_b32 s1, 0x12000
	s_nop 0
	v_addc_co_u32_e32 v49, vcc, 0, v1, vcc
	global_load_dwordx4 v[114:117], v[48:49], off
	v_add_co_u32_e32 v48, vcc, s1, v0
	s_mov_b32 s1, 0x14000
	s_nop 0
	v_addc_co_u32_e32 v49, vcc, 0, v1, vcc
	global_load_dwordx4 v[118:121], v[48:49], off
	v_add_co_u32_e32 v48, vcc, s1, v0
	s_mov_b32 s1, 0x16000
	s_nop 0
	v_addc_co_u32_e32 v49, vcc, 0, v1, vcc
	v_add_co_u32_e32 v0, vcc, s1, v0
	global_load_dwordx4 v[122:125], v[48:49], off
	s_nop 0
	v_addc_co_u32_e32 v1, vcc, 0, v1, vcc
	global_load_dwordx4 v[126:129], v[0:1], off
	s_lshl_b64 s[6:7], s[6:7], 1
	s_add_u32 s1, s28, s6
	s_addc_u32 s7, s29, s7
	s_lshl_b32 s6, s55, 8
	s_add_u32 s6, s1, s6
	s_mul_i32 s30, s30, 0xc0000
	s_addc_u32 s7, s7, 0
	s_add_u32 s72, s64, s30
	s_addc_u32 s73, s65, s31
	s_nop 0
.LBB0_128:
	v_mov_b32_e32 v100, v213
	v_cvt_pk_bf16_f32 v48, v2, v3
	v_cvt_pk_bf16_f32 v134, v54, v55
	v_bfe_u32 v0, v100, 2, 2
	v_lshrrev_b32_e32 v1, 3, v100
	v_bfe_u32 v2, v100, 1, 1
	v_and_or_b32 v54, v1, 2, v2
	v_lshlrev_b32_e32 v55, 2, v0
	v_lshlrev_b32_e32 v1, 3, v100
	v_or_b32_e32 v151, 16, v180
	v_cvt_pk_bf16_f32 v149, v52, v53
	v_and_b32_e32 v152, 8, v1
	v_or_b32_e32 v52, v55, v226
	v_or_b32_e32 v1, v0, v151
	v_lshlrev_b32_e32 v153, 8, v1
	v_bitop3_b32 v1, v55, v54, v226 bitop3:0x36
	v_or_b32_e32 v0, v0, v180
	v_bitop3_b32 v2, v52, v54, 2 bitop3:0x36
	v_cvt_pk_bf16_f32 v131, v16, v17
	v_cvt_pk_bf16_f32 v132, v18, v19
	v_lshlrev_b32_e32 v53, 8, v0
	v_lshl_add_u32 v16, v1, 4, s80
	v_lshl_add_u32 v18, v2, 4, s80
	v_cvt_pk_bf16_f32 v133, v20, v21
	v_add3_u32 v20, v16, v53, v152
	v_add3_u32 v21, v18, v53, v152
	v_cvt_pk_bf16_f32 v49, v4, v5
	v_cvt_pk_bf16_f32 v50, v6, v7
	v_cvt_pk_bf16_f32 v51, v8, v9
	ds_read_b64_tr_b16 v[0:1], v20
	ds_read_b64_tr_b16 v[2:3], v21 offset:2048
	v_or_b32_e32 v154, 0x800, v153
	v_cvt_pk_bf16_f32 v72, v22, v23
	v_add3_u32 v22, v16, v153, v152
	v_add3_u32 v23, v18, v154, v152
	v_cvt_pk_bf16_f32 v142, v10, v11
	v_cvt_pk_bf16_f32 v143, v12, v13
	v_cvt_pk_bf16_f32 v144, v14, v15
	ds_read_b64_tr_b16 v[16:17], v22
	ds_read_b64_tr_b16 v[18:19], v23
	s_waitcnt lgkmcnt(2)
	v_mfma_f32_32x32x16_bf16 v[0:15], v[48:51], v[0:3], 0
	v_cvt_pk_bf16_f32 v145, v30, v31
	v_cvt_pk_bf16_f32 v146, v64, v65
	v_cvt_pk_bf16_f32 v147, v66, v67
	v_cvt_pk_bf16_f32 v148, v68, v69
	v_cvt_pk_bf16_f32 v135, v56, v57
	v_cvt_pk_bf16_f32 v136, v58, v59
	v_cvt_pk_bf16_f32 v137, v62, v63
	ds_read_b64_tr_b16 v[244:245], v20 offset:8192
	ds_read_b64_tr_b16 v[246:247], v21 offset:10240
	s_waitcnt lgkmcnt(2)
	v_mfma_f32_32x32x16_bf16 v[0:15], v[142:145], v[16:19], v[0:15]
	v_cvt_pk_bf16_f32 v138, v32, v33
	v_cvt_pk_bf16_f32 v139, v34, v35
	v_cvt_pk_bf16_f32 v140, v36, v37
	v_cvt_pk_bf16_f32 v141, v38, v39
	v_cvt_pk_bf16_f32 v76, v40, v41
	v_cvt_pk_bf16_f32 v77, v42, v43
	ds_read_b64_tr_b16 v[16:17], v22 offset:8192
	ds_read_b64_tr_b16 v[18:19], v23 offset:8192
	s_waitcnt lgkmcnt(2)
	v_mfma_f32_32x32x16_bf16 v[0:15], v[146:149], v[244:247], v[0:15]
	v_cvt_pk_bf16_f32 v78, v44, v45
	v_cvt_pk_bf16_f32 v79, v46, v47
	v_cvt_pk_bf16_f32 v130, v60, v61
	v_cvt_pk_bf16_f32 v73, v24, v25
	v_cvt_pk_bf16_f32 v74, v26, v27
	v_cvt_pk_bf16_f32 v75, v28, v29
	ds_read_b64_tr_b16 v[244:245], v20 offset:16384
	ds_read_b64_tr_b16 v[246:247], v21 offset:18432
	s_waitcnt lgkmcnt(2)
	v_mfma_f32_32x32x16_bf16 v[0:15], v[134:137], v[16:19], v[0:15]
	v_cvt_pk_bf16_f32 v68, v70, v178
	v_cvt_pk_bf16_f32 v69, v71, v179
	v_cvt_pk_bf16_f32 v70, v182, v183
	v_cvt_pk_bf16_f32 v71, v184, v185
	v_cvt_pk_bf16_f32 v64, v186, v187
	v_cvt_pk_bf16_f32 v65, v188, v189
	ds_read_b64_tr_b16 v[16:17], v22 offset:16384
	ds_read_b64_tr_b16 v[18:19], v23 offset:16384
	s_waitcnt lgkmcnt(2)
	v_mfma_f32_32x32x16_bf16 v[0:15], v[138:141], v[244:247], v[0:15]
	v_cvt_pk_bf16_f32 v66, v190, v191
	v_cvt_pk_bf16_f32 v67, v192, v193
	s_cmp_lt_i32 s89, 0
	s_cselect_b64 s[28:29], -1, 0
	s_cmp_gt_i32 s89, -1
	s_cselect_b64 s[30:31], -1, 0
	ds_read_b64_tr_b16 v[244:245], v20 offset:24576
	ds_read_b64_tr_b16 v[246:247], v21 offset:26624
	s_waitcnt lgkmcnt(2)
	v_mfma_f32_32x32x16_bf16 v[0:15], v[76:79], v[16:19], v[0:15]
	s_and_b64 vcc, exec, s[28:29]
	ds_read_b64_tr_b16 v[16:17], v22 offset:24576
	ds_read_b64_tr_b16 v[18:19], v23 offset:24576
	s_waitcnt lgkmcnt(2)
	v_mfma_f32_32x32x16_bf16 v[0:15], v[130:133], v[244:247], v[0:15]
	ds_read_b64_tr_b16 v[244:245], v20 offset:32768
	ds_read_b64_tr_b16 v[246:247], v21 offset:34816
	s_waitcnt lgkmcnt(2)
	v_mfma_f32_32x32x16_bf16 v[0:15], v[72:75], v[16:19], v[0:15]
	ds_read_b64_tr_b16 v[16:17], v22 offset:32768
	ds_read_b64_tr_b16 v[18:19], v23 offset:32768
	s_waitcnt lgkmcnt(2)
	v_mfma_f32_32x32x16_bf16 v[0:15], v[68:71], v[244:247], v[0:15]
	s_waitcnt lgkmcnt(0)
	v_mfma_f32_32x32x16_bf16 v[0:15], v[64:67], v[16:19], v[0:15]
	v_or_b32_e32 v18, 4, v54
	v_bitop3_b32 v16, v55, v18, v226 bitop3:0x36
	v_bitop3_b32 v18, v52, v18, 2 bitop3:0x36
	v_lshl_add_u32 v32, v16, 4, s80
	v_lshl_add_u32 v34, v18, 4, s80
	v_add3_u32 v36, v32, v53, v152
	v_add3_u32 v37, v34, v53, v152
	ds_read_b64_tr_b16 v[16:17], v36
	ds_read_b64_tr_b16 v[18:19], v37 offset:2048
	v_add3_u32 v38, v32, v153, v152
	v_add3_u32 v39, v34, v154, v152
	ds_read_b64_tr_b16 v[32:33], v38
	ds_read_b64_tr_b16 v[34:35], v39
	s_waitcnt lgkmcnt(2)
	v_mfma_f32_32x32x16_bf16 v[16:31], v[48:51], v[16:19], 0
	ds_read_b64_tr_b16 v[244:245], v36 offset:8192
	ds_read_b64_tr_b16 v[246:247], v37 offset:10240
	s_waitcnt lgkmcnt(2)
	v_mfma_f32_32x32x16_bf16 v[16:31], v[142:145], v[32:35], v[16:31]
	ds_read_b64_tr_b16 v[32:33], v38 offset:8192
	ds_read_b64_tr_b16 v[34:35], v39 offset:8192
	s_waitcnt lgkmcnt(2)
	v_mfma_f32_32x32x16_bf16 v[16:31], v[146:149], v[244:247], v[16:31]
	ds_read_b64_tr_b16 v[244:245], v36 offset:16384
	ds_read_b64_tr_b16 v[246:247], v37 offset:18432
	s_waitcnt lgkmcnt(2)
	v_mfma_f32_32x32x16_bf16 v[16:31], v[134:137], v[32:35], v[16:31]
	ds_read_b64_tr_b16 v[32:33], v38 offset:16384
	ds_read_b64_tr_b16 v[34:35], v39 offset:16384
	s_waitcnt lgkmcnt(2)
	v_mfma_f32_32x32x16_bf16 v[16:31], v[138:141], v[244:247], v[16:31]
	ds_read_b64_tr_b16 v[244:245], v36 offset:24576
	ds_read_b64_tr_b16 v[246:247], v37 offset:26624
	s_waitcnt lgkmcnt(2)
	v_mfma_f32_32x32x16_bf16 v[16:31], v[76:79], v[32:35], v[16:31]
	ds_read_b64_tr_b16 v[32:33], v38 offset:24576
	ds_read_b64_tr_b16 v[34:35], v39 offset:24576
	s_waitcnt lgkmcnt(2)
	v_mfma_f32_32x32x16_bf16 v[16:31], v[130:133], v[244:247], v[16:31]
	ds_read_b64_tr_b16 v[244:245], v36 offset:32768
	ds_read_b64_tr_b16 v[246:247], v37 offset:34816
	s_waitcnt lgkmcnt(2)
	v_mfma_f32_32x32x16_bf16 v[16:31], v[72:75], v[32:35], v[16:31]
	ds_read_b64_tr_b16 v[32:33], v38 offset:32768
	ds_read_b64_tr_b16 v[34:35], v39 offset:32768
	s_waitcnt lgkmcnt(2)
	v_mfma_f32_32x32x16_bf16 v[16:31], v[68:71], v[244:247], v[16:31]
	s_waitcnt lgkmcnt(0)
	v_mfma_f32_32x32x16_bf16 v[16:31], v[64:67], v[32:35], v[16:31]
	v_or_b32_e32 v34, 8, v54
	v_bitop3_b32 v32, v55, v34, v226 bitop3:0x36
	v_bitop3_b32 v34, v52, v34, 2 bitop3:0x36
	v_lshl_add_u32 v56, v32, 4, s80
	v_lshl_add_u32 v58, v34, 4, s80
	v_add3_u32 v60, v56, v53, v152
	v_add3_u32 v61, v58, v53, v152
	ds_read_b64_tr_b16 v[32:33], v60
	ds_read_b64_tr_b16 v[34:35], v61 offset:2048
	v_add3_u32 v62, v56, v153, v152
	v_add3_u32 v63, v58, v154, v152
	ds_read_b64_tr_b16 v[56:57], v62
	ds_read_b64_tr_b16 v[58:59], v63
	s_waitcnt lgkmcnt(2)
	v_mfma_f32_32x32x16_bf16 v[32:47], v[48:51], v[32:35], 0
	ds_read_b64_tr_b16 v[244:245], v60 offset:8192
	ds_read_b64_tr_b16 v[246:247], v61 offset:10240
	s_waitcnt lgkmcnt(2)
	v_mfma_f32_32x32x16_bf16 v[32:47], v[142:145], v[56:59], v[32:47]
	ds_read_b64_tr_b16 v[56:57], v62 offset:8192
	ds_read_b64_tr_b16 v[58:59], v63 offset:8192
	s_waitcnt lgkmcnt(2)
	v_mfma_f32_32x32x16_bf16 v[32:47], v[146:149], v[244:247], v[32:47]
	ds_read_b64_tr_b16 v[244:245], v60 offset:16384
	ds_read_b64_tr_b16 v[246:247], v61 offset:18432
	s_waitcnt lgkmcnt(2)
	v_mfma_f32_32x32x16_bf16 v[32:47], v[134:137], v[56:59], v[32:47]
	ds_read_b64_tr_b16 v[56:57], v62 offset:16384
	ds_read_b64_tr_b16 v[58:59], v63 offset:16384
	s_waitcnt lgkmcnt(2)
	v_mfma_f32_32x32x16_bf16 v[32:47], v[138:141], v[244:247], v[32:47]
	ds_read_b64_tr_b16 v[244:245], v60 offset:24576
	ds_read_b64_tr_b16 v[246:247], v61 offset:26624
	s_waitcnt lgkmcnt(2)
	v_mfma_f32_32x32x16_bf16 v[32:47], v[76:79], v[56:59], v[32:47]
	ds_read_b64_tr_b16 v[56:57], v62 offset:24576
	ds_read_b64_tr_b16 v[58:59], v63 offset:24576
	s_waitcnt lgkmcnt(2)
	v_mfma_f32_32x32x16_bf16 v[32:47], v[130:133], v[244:247], v[32:47]
	ds_read_b64_tr_b16 v[244:245], v60 offset:32768
	ds_read_b64_tr_b16 v[246:247], v61 offset:34816
	s_waitcnt lgkmcnt(2)
	v_mfma_f32_32x32x16_bf16 v[32:47], v[72:75], v[56:59], v[32:47]
	ds_read_b64_tr_b16 v[56:57], v62 offset:32768
	ds_read_b64_tr_b16 v[58:59], v63 offset:32768
	s_waitcnt lgkmcnt(2)
	v_mfma_f32_32x32x16_bf16 v[32:47], v[68:71], v[244:247], v[32:47]
	s_waitcnt lgkmcnt(0)
	v_mfma_f32_32x32x16_bf16 v[32:47], v[64:67], v[56:59], v[32:47]
	v_or_b32_e32 v56, 12, v54
	v_bitop3_b32 v54, v55, v56, v226 bitop3:0x36
	v_bitop3_b32 v52, v52, v56, 2 bitop3:0x36
	v_lshl_add_u32 v155, v54, 4, s80
	v_lshl_add_u32 v158, v52, 4, s80
	v_add3_u32 v160, v155, v53, v152
	v_add3_u32 v161, v158, v53, v152
	ds_read_b64_tr_b16 v[54:55], v160
	ds_read_b64_tr_b16 v[56:57], v161 offset:2048
	v_add3_u32 v153, v155, v153, v152
	ds_read_b64_tr_b16 v[156:157], v153
	s_waitcnt lgkmcnt(1)
	v_mfma_f32_32x32x16_bf16 v[48:63], v[48:51], v[54:57], 0
	v_add3_u32 v152, v158, v154, v152
	ds_read_b64_tr_b16 v[158:159], v152
	ds_read_b64_tr_b16 v[244:245], v160 offset:8192
	ds_read_b64_tr_b16 v[246:247], v161 offset:10240
	s_waitcnt lgkmcnt(2)
	v_mfma_f32_32x32x16_bf16 v[48:63], v[142:145], v[156:159], v[48:63]
	ds_read_b64_tr_b16 v[156:157], v153 offset:8192
	ds_read_b64_tr_b16 v[158:159], v152 offset:8192
	s_waitcnt lgkmcnt(2)
	v_mfma_f32_32x32x16_bf16 v[48:63], v[146:149], v[244:247], v[48:63]
	ds_read_b64_tr_b16 v[244:245], v160 offset:16384
	ds_read_b64_tr_b16 v[246:247], v161 offset:18432
	s_waitcnt lgkmcnt(2)
	v_mfma_f32_32x32x16_bf16 v[48:63], v[134:137], v[156:159], v[48:63]
	ds_read_b64_tr_b16 v[156:157], v153 offset:16384
	ds_read_b64_tr_b16 v[158:159], v152 offset:16384
	s_waitcnt lgkmcnt(2)
	v_mfma_f32_32x32x16_bf16 v[48:63], v[138:141], v[244:247], v[48:63]
	ds_read_b64_tr_b16 v[244:245], v160 offset:24576
	ds_read_b64_tr_b16 v[246:247], v161 offset:26624
	s_waitcnt lgkmcnt(2)
	v_mfma_f32_32x32x16_bf16 v[48:63], v[76:79], v[156:159], v[48:63]
	ds_read_b64_tr_b16 v[156:157], v153 offset:24576
	ds_read_b64_tr_b16 v[158:159], v152 offset:24576
	s_waitcnt lgkmcnt(2)
	v_mfma_f32_32x32x16_bf16 v[48:63], v[130:133], v[244:247], v[48:63]
	v_ashrrev_i32_e32 v133, 3, v100
	v_lshlrev_b32_e32 v100, 4, v100
	v_and_b32_e32 v100, 0x70, v100
	v_lshl_add_u32 v132, v227, 1, s79
	v_add_u32_e32 v134, s79, v100
	v_lshl_add_u64 v[130:131], s[50:51], 0, v[100:101]
	ds_read_b64_tr_b16 v[244:245], v160 offset:32768
	ds_read_b64_tr_b16 v[246:247], v161 offset:34816
	s_waitcnt lgkmcnt(2)
	v_mfma_f32_32x32x16_bf16 v[48:63], v[72:75], v[156:159], v[48:63]
	v_lshlrev_b32_e32 v100, 9, v226
	v_add_u32_e32 v100, v132, v100
	ds_read_b64_tr_b16 v[156:157], v153 offset:32768
	ds_read_b64_tr_b16 v[158:159], v152 offset:32768
	s_waitcnt lgkmcnt(2)
	v_mfma_f32_32x32x16_bf16 v[48:63], v[68:71], v[244:247], v[48:63]
	s_waitcnt lgkmcnt(0)
	v_mfma_f32_32x32x16_bf16 v[48:63], v[64:67], v[156:159], v[48:63]
	v_lshl_add_u32 v64, v180, 2, s78
	ds_read_b128 v[76:79], v64
	ds_read_b128 v[72:75], v64 offset:32
	ds_read_b128 v[68:71], v64 offset:64
	ds_read_b128 v[64:67], v64 offset:96
	s_waitcnt lgkmcnt(3)
	v_mul_f32_e32 v0, v0, v76
	v_cvt_pk_bf16_f32 v0, v0, s0
	ds_write_b16 v100, v0
	v_mul_f32_e32 v0, v16, v76
	v_cvt_pk_bf16_f32 v0, v0, s0
	ds_write_b16 v100, v0 offset:64
	v_mul_f32_e32 v0, v1, v77
	v_cvt_pk_bf16_f32 v0, v0, s0
	ds_write_b16 v100, v0 offset:128
	v_mul_f32_e32 v0, v17, v77
	v_cvt_pk_bf16_f32 v0, v0, s0
	ds_write_b16 v100, v0 offset:192
	v_mul_f32_e32 v0, v2, v78
	v_cvt_pk_bf16_f32 v0, v0, s0
	ds_write_b16 v100, v0 offset:256
	v_mul_f32_e32 v0, v18, v78
	v_cvt_pk_bf16_f32 v0, v0, s0
	ds_write_b16 v100, v0 offset:320
	v_mul_f32_e32 v0, v3, v79
	v_cvt_pk_bf16_f32 v0, v0, s0
	ds_write_b16 v100, v0 offset:384
	v_mul_f32_e32 v0, v19, v79
	v_cvt_pk_bf16_f32 v0, v0, s0
	ds_write_b16 v100, v0 offset:448
	s_waitcnt lgkmcnt(10)
	v_mul_f32_e32 v0, v4, v72
	v_cvt_pk_bf16_f32 v0, v0, s0
	ds_write_b16 v100, v0 offset:1024
	v_mul_f32_e32 v0, v20, v72
	v_cvt_pk_bf16_f32 v0, v0, s0
	ds_write_b16 v100, v0 offset:1088
	v_mul_f32_e32 v0, v5, v73
	v_cvt_pk_bf16_f32 v0, v0, s0
	ds_write_b16 v100, v0 offset:1152
	v_mul_f32_e32 v0, v21, v73
	v_cvt_pk_bf16_f32 v0, v0, s0
	ds_write_b16 v100, v0 offset:1216
	v_mul_f32_e32 v0, v6, v74
	v_cvt_pk_bf16_f32 v0, v0, s0
	ds_write_b16 v100, v0 offset:1280
	v_mul_f32_e32 v0, v22, v74
	v_cvt_pk_bf16_f32 v0, v0, s0
	ds_write_b16 v100, v0 offset:1344
	v_mul_f32_e32 v0, v7, v75
	v_cvt_pk_bf16_f32 v0, v0, s0
	ds_write_b16 v100, v0 offset:1408
	v_mul_f32_e32 v0, v23, v75
	v_cvt_pk_bf16_f32 v0, v0, s0
	ds_write_b16 v100, v0 offset:1472
	v_lshlrev_b32_e32 v0, 7, v151
	v_add_u32_e32 v5, v132, v0
	s_waitcnt lgkmcnt(14)
	v_mul_f32_e32 v0, v8, v68
	v_cvt_pk_bf16_f32 v0, v0, s0
	ds_write_b16 v5, v0
	v_mul_f32_e32 v0, v24, v68
	v_cvt_pk_bf16_f32 v0, v0, s0
	ds_write_b16 v5, v0 offset:64
	v_mul_f32_e32 v0, v9, v69
	v_cvt_pk_bf16_f32 v0, v0, s0
	ds_write_b16 v100, v0 offset:2176
	v_mul_f32_e32 v0, v25, v69
	v_cvt_pk_bf16_f32 v0, v0, s0
	ds_write_b16 v100, v0 offset:2240
	v_mul_f32_e32 v0, v10, v70
	v_cvt_pk_bf16_f32 v0, v0, s0
	ds_write_b16 v100, v0 offset:2304
	v_mul_f32_e32 v0, v26, v70
	v_cvt_pk_bf16_f32 v0, v0, s0
	ds_write_b16 v100, v0 offset:2368
	v_mul_f32_e32 v0, v11, v71
	v_cvt_pk_bf16_f32 v0, v0, s0
	ds_write_b16 v100, v0 offset:2432
	v_mul_f32_e32 v0, v27, v71
	v_cvt_pk_bf16_f32 v0, v0, s0
	ds_write_b16 v100, v0 offset:2496
	v_mul_f32_e32 v0, v12, v64
	v_cvt_pk_bf16_f32 v0, v0, s0
	ds_write_b16 v100, v0 offset:3072
	v_mul_f32_e32 v0, v28, v64
	v_cvt_pk_bf16_f32 v0, v0, s0
	ds_write_b16 v100, v0 offset:3136
	v_mul_f32_e32 v0, v13, v65
	v_cvt_pk_bf16_f32 v0, v0, s0
	ds_write_b16 v100, v0 offset:3200
	v_mul_f32_e32 v0, v29, v65
	v_cvt_pk_bf16_f32 v0, v0, s0
	ds_write_b16 v100, v0 offset:3264
	v_mul_f32_e32 v0, v14, v66
	v_cvt_pk_bf16_f32 v0, v0, s0
	ds_write_b16 v100, v0 offset:3328
	v_mul_f32_e32 v0, v30, v66
	v_cvt_pk_bf16_f32 v0, v0, s0
	ds_write_b16 v100, v0 offset:3392
	v_mul_f32_e32 v0, v15, v67
	v_cvt_pk_bf16_f32 v0, v0, s0
	ds_write_b16 v100, v0 offset:3456
	v_mul_f32_e32 v0, v31, v67
	v_cvt_pk_bf16_f32 v0, v0, s0
	ds_write_b16 v100, v0 offset:3520
	v_add_u32_e32 v0, s85, v133
	v_add_u32_e32 v1, 8, v133
	v_add_u32_e32 v2, 16, v133
	v_add_u32_e32 v9, 24, v133
	v_lshl_add_u32 v7, v133, 7, v134
	v_mul_lo_u32 v8, v0, s84
	v_add_u32_e32 v6, s85, v1
	v_lshl_add_u32 v4, v1, 7, v134
	v_add_u32_e32 v3, s85, v2
	v_lshl_add_u32 v2, v2, 7, v134
	v_add_u32_e32 v1, s85, v9
	v_lshl_add_u32 v0, v9, 7, v134
	s_cbranch_vccnz .LBB0_130
	ds_read_b128 v[10:13], v7
	v_add_u32_e32 v14, s67, v8
	v_ashrrev_i32_e32 v15, 31, v14
	v_lshlrev_b64 v[14:15], 13, v[14:15]
	v_lshl_add_u64 v[14:15], v[130:131], 0, v[14:15]
	s_waitcnt lgkmcnt(0)
	global_store_dwordx4 v[14:15], v[10:13], off
	v_mul_lo_u32 v9, v6, s84
	ds_read_b128 v[10:13], v4
	v_add_u32_e32 v14, s67, v9
	v_ashrrev_i32_e32 v15, 31, v14
	v_lshlrev_b64 v[14:15], 13, v[14:15]
	v_lshl_add_u64 v[14:15], v[130:131], 0, v[14:15]
	s_waitcnt lgkmcnt(0)
	global_store_dwordx4 v[14:15], v[10:13], off
	v_mul_lo_u32 v9, v3, s84
	ds_read_b128 v[10:13], v2
	v_add_u32_e32 v14, s67, v9
	v_ashrrev_i32_e32 v15, 31, v14
	v_lshlrev_b64 v[14:15], 13, v[14:15]
	v_lshl_add_u64 v[14:15], v[130:131], 0, v[14:15]
	s_waitcnt lgkmcnt(0)
	global_store_dwordx4 v[14:15], v[10:13], off
	v_mul_lo_u32 v9, v1, s84
	ds_read_b128 v[10:13], v0
	v_add_u32_e32 v14, s67, v9
	v_ashrrev_i32_e32 v15, 31, v14
	v_lshlrev_b64 v[14:15], 13, v[14:15]
	v_lshl_add_u64 v[14:15], v[130:131], 0, v[14:15]
	s_waitcnt lgkmcnt(0)
	global_store_dwordx4 v[14:15], v[10:13], off
